# attention unit prologue: Q loads and first K/V tile LDS-DMAs issued at the top of the unit, bias table / far-bias loads hoisted next to the bound loads
# speedup vs baseline: 1.0177x; 1.0032x over previous
; template <bool FIXED> __device__ __forceinline__ void attn_unit(int b, int h, int qb, const bf16* __restrict__ P, bf16* __restrict__ MIX, const float* __restrict__ BT, const float* __restrict__ subg, ...
;     ...
;   for (int i = tid; i < 768; i += 512) btl[i] = BT[(size_t)h * 768 + i] - (FIXED ? sref : 0.f);
;   const float* bt = btl + m * 384 + 128;
;   const float c31 = BT[(size_t)h * 768 + m * 384 + 128 + 127] - (FIXED ? sref : 0.f);
;   f32x16 cfar, czero = f32x16{};
; #pragma unroll
;   for (int r = 0; r < 16; ++r) cfar[r] = FIXED ? c31 : 0.f;
;   float m_reg = -1e30f, l_reg = 0.f; f32x16 o[4] = {}; bf16x8 qr[4];
;   const bf16* Qw = P + (rowbase + qw0 + r32) * PW + h * 128 + m * 64 + hi * 8;
; #pragma unroll
;   for (int d0 = 0; d0 < 4; ++d0) qr[d0] = *reinterpret_cast<const bf16x8*>(Qw + d0 * 16);
;   const bf16* Kh = P + rowbase * PW + 1024 + h * 128; const bf16* Vh = P + rowbase * PW + 2048 + h * 128;
;   unsigned ksrc[2], vsrc[2];
; #pragma unroll
;   for (int i = 0; i < 2; ++i) { const int pk = wid * 2 + i;
;     { const int row = 4 * pk + (lane >> 4), cc = lane & 15; ksrc[i] = (unsigned)(row * PW + ((cc ^ (row & 7)) * 8)); }
;     { const int ob = pk * 1024 + lane * 16, sub = ob >> 9, kk = (sub >> 2) * 8 + ((ob & 511) >> 6), k = (kk & ~0xC) | ((kk & 4) << 1) | ((kk & 8) >> 1), c = (sub & 3) * 32 + ((ob & 63) >> 1);
;       vsrc[i] = (unsigned)(k * PW + c); } }
;   typedef __attribute__((address_space(3))) unsigned lds_u32;
;   typedef __attribute__((address_space(3))) unsigned char lds_u8;
;   lds_u8* const ring = (lds_u8*)lds + wid * 2048;
;     ...
;   const lds_cptr vp0 = (lds_cptr)lds + SHM_K + v_rd_base(lane);
;     ...
;   f32x16 p0, p1; float al, ca; bf16x8 pa0, pa1, pa2, pa3; const int NT = 2 * qb + 2;
;     ...
;   const int NTT = ATT_REP * NT;
;   DMA_TILE(0, 0); DMA_TILE(1, 1);
;   WAIT_BAR(4);
; __global__ void __launch_bounds__(NWAVES * 64, 2) hybrid_fwd(Args args) {
;     ...
;                 {   const int qb = half == 0 ? 15 - s : s, hh = bh % NH;
;                     float bm = fmaxf(fmaxf(BT[hh * 768 + 128 + lane], BT[hh * 768 + 128 + 64 + lane]), fmaxf(BT[hh * 768 + 384 + 128 + lane], BT[hh * 768 + 384 + 128 + 64 + lane]));
; #pragma unroll
;                     for (int o = 1; o < 64; o <<= 1) bm = fmaxf(bm, __shfl_xor(bm, o));
;                     const float sref = 11.8f * gqk + bm + 0.25f;
.LBB0_301:
	global_load_dword v0, v[132:133], off
	global_load_dword v1, v[130:131], off
	global_load_dword v2, v[128:129], off offset:512
	global_load_dword v3, v[128:129], off offset:768
	s_and_b64 s[0:1], s[30:31], exec
	s_cselect_b32 s73, s66, s3
	v_lshlrev_b32_e32 v100, 2, v169
	v_readfirstlane_b32 s8, v169
	global_load_dword v102, v100, s[10:11]
	global_load_dword v103, v100, s[10:11] offset:2048
	s_ashr_i32 s8, s8, 8
	s_mul_i32 s8, s8, 0x600
	s_add_u32 s8, s10, s8
	s_addc_u32 s9, s11, 0
	global_load_dword v104, v145, s[8:9] offset:1020
	s_mov_b32 s0, 0x42200000
	s_or_b32 s71, s6, s67
	s_lshl_b32 s34, s73, 7
	v_mov_b32_e32 v80, v169
	v_readfirstlane_b32 s25, v169
	s_nop 1
	s_ashr_i32 s1, s25, 6
	s_ashr_i32 s26, s25, 8
	s_and_b32 s24, s1, 3
	s_lshl_b32 s99, s24, 5
	s_or_b32 s99, s99, s34
	v_and_b32_e32 v134, 31, v80
	s_or_b32 s22, s54, s99
	v_bfe_u32 v167, v80, 5, 1
	v_lshlrev_b32_e32 v144, 4, v167
	s_lshl_b32 s8, s1, 3
	v_bfe_u32 v93, v80, 2, 2
	v_and_b32_e32 v168, 63, v80
	v_lshlrev_b32_e32 v166, 3, v168
	v_bfe_u32 v92, v80, 4, 2
	v_and_b32_e32 v95, 32, v80
	v_and_b32_e32 v96, 24, v166
	v_lshlrev_b32_e32 v99, 4, v80
	v_mov_b32_e32 v89, v145
	v_mov_b32_e32 v85, v145
	v_mov_b32_e32 v87, v145
	v_or_b32_e32 v81, s22, v134
	v_mov_b64_e32 v[82:83], s[16:17]
	v_mad_u64_u32 v[82:83], s[6:7], v81, s70, v[82:83]
	s_lshl_b32 s6, s26, 6
	v_mad_i32_i24 v83, s55, v196, v83
	s_ashr_i32 s7, s6, 31
	v_lshl_add_u64 v[82:83], s[6:7], 1, v[82:83]
	v_lshl_add_u64 v[82:83], v[82:83], 0, v[144:145]
	global_load_dwordx4 v[112:115], v[82:83], off
	global_load_dwordx4 v[116:119], v[82:83], off offset:32
	global_load_dwordx4 v[120:123], v[82:83], off offset:64
	global_load_dwordx4 v[124:127], v[82:83], off offset:96
	v_lshrrev_b32_e32 v82, 2, v80
	s_and_b32 s6, s8, -16
	v_and_b32_e32 v94, 4, v82
	s_lshl_b32 s7, s1, 3
	s_and_b32 s7, s7, 8
	v_or3_b32 v82, v94, v93, s6
	v_or_b32_e32 v82, s7, v82
	v_mul_lo_u32 v82, v82, s35
	v_or3_b32 v84, v82, v95, v96
	v_or_b32_e32 v82, s8, v92
	v_bitop3_b32 v83, v92, v80, 15 bitop3:0x78
	v_and_b32_e32 v81, 15, v80
	v_mul_lo_u32 v82, v82, s35
	v_lshlrev_b32_e32 v97, 3, v83
	v_or_b32_e32 v88, v82, v97
	v_or_b32_e32 v82, 4, v92
	v_bitop3_b32 v81, v92, v81, 4 bitop3:0x36
	v_or_b32_e32 v82, s8, v82
	v_lshlrev_b32_e32 v98, 3, v81
	v_mul_lo_u32 v82, v82, s35
	s_lshl_b32 s8, s1, 11
	v_lshlrev_b64 v[80:81], 1, v[88:89]
	v_or_b32_e32 v86, v82, v98
	s_add_i32 s27, s8, 0
	v_lshl_add_u64 v[88:89], s[18:19], 0, v[80:81]
	v_or_b32_e32 v82, 64, v84
	s_add_i32 s8, s27, 0x4000
	v_lshl_add_u64 v[88:89], v[88:89], 0, s[36:37]
	s_mov_b32 m0, s27
	v_lshlrev_b64 v[84:85], 1, v[84:85]
	v_lshlrev_b64 v[86:87], 1, v[86:87]
	global_load_lds_dwordx4 v[88:89], off
	v_lshl_add_u64 v[88:89], s[20:21], 0, v[84:85]
	s_mov_b32 m0, s8
	v_lshl_add_u64 v[90:91], s[18:19], 0, v[86:87]
	global_load_lds_dwordx4 v[88:89], off
	v_lshl_add_u64 v[90:91], v[90:91], 0, s[36:37]
	s_add_i32 m0, s27, 0x400
	v_lshl_add_u64 v[88:89], v[88:89], 0, s[94:95]
	global_load_lds_dwordx4 v[90:91], off
	s_add_i32 m0, s27, 0x4400
	s_add_i32 s8, s27, 0xc000
	global_load_lds_dwordx4 v[88:89], off
	s_add_i32 m0, s27, 0x8000
	v_lshl_add_u64 v[80:81], s[88:89], 0, v[80:81]
	global_load_lds_dwordx4 v[80:81], off
	v_lshl_add_u64 v[80:81], s[90:91], 0, v[84:85]
	s_mov_b32 m0, s8
	v_mov_b32_e32 v83, v145
	global_load_lds_dwordx4 v[80:81], off
	v_lshl_add_u64 v[80:81], s[88:89], 0, v[86:87]
	s_add_i32 m0, s27, 0x8400
	s_nop 0
	global_load_lds_dwordx4 v[80:81], off
	v_lshl_add_u64 v[80:81], v[82:83], 1, s[90:91]
	s_add_i32 m0, s27, 0xc400
	s_nop 0
	global_load_lds_dwordx4 v[80:81], off
	s_waitcnt vmcnt(18)
	v_max_f32_e32 v0, v0, v0
	s_waitcnt vmcnt(17)
	v_max_f32_e32 v1, v1, v1
	v_max_f32_e32 v0, v1, v0
	s_waitcnt vmcnt(15)
	v_max3_f32 v0, v2, v3, v0
	ds_bpermute_b32 v1, v135, v0
	s_waitcnt lgkmcnt(0)
	v_max_f32_e32 v1, v1, v1
	v_max_f32_e32 v0, v0, v1
	ds_bpermute_b32 v1, v142, v0
	s_waitcnt lgkmcnt(0)
	v_max_f32_e32 v1, v1, v1
	v_max_f32_e32 v0, v0, v1
	ds_bpermute_b32 v1, v143, v0
	s_waitcnt lgkmcnt(0)
	v_max_f32_e32 v1, v1, v1
	v_max_f32_e32 v0, v0, v1
	ds_bpermute_b32 v1, v160, v0
	s_waitcnt lgkmcnt(0)
	v_max_f32_e32 v1, v1, v1
	v_max_f32_e32 v0, v0, v1
	ds_bpermute_b32 v1, v161, v0
	s_waitcnt lgkmcnt(0)
	v_max_f32_e32 v1, v1, v1
	v_max_f32_e32 v0, v0, v1
	ds_bpermute_b32 v1, v162, v0
	s_waitcnt lgkmcnt(0)
	v_max_f32_e32 v1, v1, v1
	v_max_f32_e32 v0, v0, v1
	v_add_f32_e32 v0, v164, v0
	v_add_f32_e32 v2, 0x3e800000, v0
	v_cmp_ge_f32_e32 vcc, s0, v2
	s_and_saveexec_b64 s[0:1], vcc
	s_xor_b64 s[40:41], exec, s[0:1]
	s_cbranch_execz .LBB0_341
; __device__ __forceinline__ int v_rd_base(int lane) { return ((lane & 3) << 3) | (((lane >> 2) & 3) << 6) | (((lane >> 4) & 1) << 5) | (((lane >> 5) & 1) << 8); }
; #define WAIT_BAR(N) asm volatile("s_waitcnt vmcnt(" #N ") lgkmcnt(0)\n\ts_barrier" ::: "memory")
; template <bool FIXED> __device__ __forceinline__ void attn_unit(int b, int h, int qb, const bf16* __restrict__ P, bf16* __restrict__ MIX, const float* __restrict__ BT, const float* __restrict__ subg, ...
;     ...
;   for (int i = tid; i < 768; i += 512) btl[i] = BT[(size_t)h * 768 + i] - (FIXED ? sref : 0.f);
;   const float* bt = btl + m * 384 + 128;
;   const float c31 = BT[(size_t)h * 768 + m * 384 + 128 + 127] - (FIXED ? sref : 0.f);
;   f32x16 cfar, czero = f32x16{};
; #pragma unroll
;   for (int r = 0; r < 16; ++r) cfar[r] = FIXED ? c31 : 0.f;
;   float m_reg = -1e30f, l_reg = 0.f; f32x16 o[4] = {}; bf16x8 qr[4];
;   const bf16* Qw = P + (rowbase + qw0 + r32) * PW + h * 128 + m * 64 + hi * 8;
; #pragma unroll
;   for (int d0 = 0; d0 < 4; ++d0) qr[d0] = *reinterpret_cast<const bf16x8*>(Qw + d0 * 16);
;   const bf16* Kh = P + rowbase * PW + 1024 + h * 128; const bf16* Vh = P + rowbase * PW + 2048 + h * 128;
;   unsigned ksrc[2], vsrc[2];
; #pragma unroll
;   for (int i = 0; i < 2; ++i) { const int pk = wid * 2 + i;
;     { const int row = 4 * pk + (lane >> 4), cc = lane & 15; ksrc[i] = (unsigned)(row * PW + ((cc ^ (row & 7)) * 8)); }
;     { const int ob = pk * 1024 + lane * 16, sub = ob >> 9, kk = (sub >> 2) * 8 + ((ob & 511) >> 6), k = (kk & ~0xC) | ((kk & 4) << 1) | ((kk & 8) >> 1), c = (sub & 3) * 32 + ((ob & 63) >> 1);
;       vsrc[i] = (unsigned)(k * PW + c); } }
;   typedef __attribute__((address_space(3))) unsigned lds_u32;
;   typedef __attribute__((address_space(3))) unsigned char lds_u8;
;   lds_u8* const ring = (lds_u8*)lds + wid * 2048;
;     ...
;   const lds_cptr vp0 = (lds_cptr)lds + SHM_K + v_rd_base(lane);
;     ...
;   f32x16 p0, p1; float al, ca; bf16x8 pa0, pa1, pa2, pa3; const int NT = 2 * qb + 2;
;     ...
;   const int NTT = ATT_REP * NT;
;   DMA_TILE(0, 0); DMA_TILE(1, 1);
;   WAIT_BAR(4);
;   int slot = 0;
	v_mov_b32_e32 v0, v169
	s_nop 0
	v_readfirstlane_b32 s25, v0
	s_waitcnt vmcnt(12)
	v_sub_f32_e32 v102, v102, v2
	v_add_u32_e32 v101, s2, v100
	ds_write_b32 v101, v102
	v_cmp_gt_u32_e32 vcc, 0x100, v169
	s_and_saveexec_b64 s[0:1], vcc
	v_sub_f32_e32 v103, v103, v2
	ds_write_b32 v101, v103 offset:2048
	s_mov_b64 exec, s[0:1]
	s_ashr_i32 s1, s25, 6
	s_ashr_i32 s26, s25, 8
	s_and_b32 s24, s1, 3
	s_mul_i32 s6, s26, 0x180
	s_lshl_b32 s0, s24, 5
	s_ashr_i32 s7, s6, 31
	s_or_b32 s29, s0, s34
	s_lshl_b64 s[6:7], s[6:7], 2
	s_add_u32 s6, s10, s6
	s_addc_u32 s7, s11, s7
	v_and_b32_e32 v134, 31, v0
	s_or_b32 s22, s54, s29
	v_bfe_u32 v167, v0, 5, 1
	v_lshlrev_b32_e32 v144, 4, v167
	s_lshl_b32 s8, s1, 3
	v_bfe_u32 v13, v0, 2, 2
	v_and_b32_e32 v168, 63, v0
	v_lshlrev_b32_e32 v166, 3, v168
	v_bfe_u32 v12, v0, 4, 2
	v_and_b32_e32 v15, 32, v0
	v_and_b32_e32 v16, 24, v166
	v_lshlrev_b32_e32 v19, 4, v0
	v_mov_b32_e32 v9, v145
	v_mov_b32_e32 v5, v145
	v_mov_b32_e32 v7, v145
	s_add_i32 s0, s34, s0
	s_lshl_b32 s38, s73, 9
	v_mov_b32_e32 v176, 0
	s_mov_b32 s23, s55
	s_lshl_b32 s28, s73, 1
	s_addk_i32 s29, 0xff51
	v_lshlrev_b32_e32 v171, 8, v134
	s_addk_i32 s38, 0x200
	s_mov_b32 s39, 0
	s_mov_b32 s44, 0
	s_mov_b32 s45, 0
	s_mov_b32 s56, 0
	v_mov_b32_e32 v22, v176
	v_mov_b32_e32 v23, v176
	v_mov_b32_e32 v24, v176
	v_mov_b32_e32 v25, v176
	v_mov_b32_e32 v26, v176
	v_mov_b32_e32 v27, v176
	v_mov_b32_e32 v28, v176
	v_mov_b32_e32 v29, v176
	v_mov_b32_e32 v30, v176
	v_mov_b32_e32 v31, v176
	v_mov_b32_e32 v32, 0
	v_mov_b32_e32 v33, v176
	v_mov_b32_e32 v34, v176
	v_mov_b32_e32 v35, v176
	v_mov_b32_e32 v36, v176
	v_mov_b32_e32 v37, v176
	v_mov_b32_e32 v38, v176
	v_mov_b32_e32 v39, v176
	v_mov_b32_e32 v40, v176
	v_mov_b32_e32 v41, v176
	v_mov_b32_e32 v42, v176
	v_mov_b32_e32 v43, v176
	v_mov_b32_e32 v44, v176
	v_mov_b32_e32 v45, v176
	v_mov_b32_e32 v46, v176
	v_mov_b32_e32 v47, v176
	v_mov_b32_e32 v48, 0
	v_mov_b32_e32 v49, v176
	v_mov_b32_e32 v50, v176
	v_mov_b32_e32 v51, v176
	v_mov_b32_e32 v52, v176
	v_mov_b32_e32 v53, v176
	v_mov_b32_e32 v54, v176
	v_mov_b32_e32 v55, v176
	v_mov_b32_e32 v56, v176
	v_mov_b32_e32 v57, v176
	v_mov_b32_e32 v58, v176
	v_mov_b32_e32 v59, v176
	v_mov_b32_e32 v60, v176
	v_mov_b32_e32 v61, v176
	v_mov_b32_e32 v62, v176
	v_mov_b32_e32 v63, v176
	s_waitcnt vmcnt(12)
	v_sub_f32_e32 v64, v104, v2
	v_or_b32_e32 v1, s22, v134
	v_mov_b64_e32 v[2:3], s[16:17]
	v_mad_u64_u32 v[2:3], s[6:7], v1, s70, v[2:3]
	s_lshl_b32 s6, s26, 6
	v_mad_i32_i24 v3, s55, v196, v3
	s_ashr_i32 s7, s6, 31
	v_lshl_add_u64 v[2:3], s[6:7], 1, v[2:3]
	v_lshl_add_u64 v[2:3], v[2:3], 0, v[144:145]
	v_lshrrev_b32_e32 v2, 2, v0
	s_and_b32 s6, s8, -16
	v_and_b32_e32 v14, 4, v2
	s_lshl_b32 s7, s1, 3
	s_and_b32 s7, s7, 8
	v_or3_b32 v2, v14, v13, s6
	v_or_b32_e32 v2, s7, v2
	v_mul_lo_u32 v2, v2, s35
	v_or3_b32 v4, v2, v15, v16
	v_or_b32_e32 v2, s8, v12
	v_bitop3_b32 v3, v12, v0, 15 bitop3:0x78
	v_and_b32_e32 v1, 15, v0
	v_mul_lo_u32 v2, v2, s35
	v_lshlrev_b32_e32 v17, 3, v3
	v_or_b32_e32 v8, v2, v17
	v_or_b32_e32 v2, 4, v12
	v_bitop3_b32 v1, v12, v1, 4 bitop3:0x36
	v_or_b32_e32 v2, s8, v2
	v_lshlrev_b32_e32 v18, 3, v1
	v_and_b32_e32 v1, 0xc0, v19
	v_lshlrev_b32_e32 v0, 1, v0
	v_mul_lo_u32 v2, v2, s35
	s_lshl_b32 s8, s1, 11
	v_and_b32_e32 v20, 32, v0
	v_add3_u32 v21, 0, v16, v1
	v_lshlrev_b64 v[0:1], 1, v[8:9]
	v_or_b32_e32 v6, v2, v18
	s_add_i32 s27, s8, 0
	v_lshl_add_u64 v[8:9], s[18:19], 0, v[0:1]
	v_or_b32_e32 v2, 64, v4
	s_add_i32 s8, s27, 0x4000
	v_lshl_add_u64 v[8:9], v[8:9], 0, s[36:37]
	s_mov_b32 m0, s27
	v_lshlrev_b64 v[4:5], 1, v[4:5]
	v_lshlrev_b64 v[6:7], 1, v[6:7]
	v_lshl_add_u64 v[8:9], s[20:21], 0, v[4:5]
	s_mov_b32 m0, s8
	v_lshl_add_u64 v[10:11], s[18:19], 0, v[6:7]
	v_lshl_add_u64 v[10:11], v[10:11], 0, s[36:37]
	s_add_i32 m0, s27, 0x400
	v_lshl_add_u64 v[8:9], v[8:9], 0, s[94:95]
	s_add_i32 m0, s27, 0x4400
	s_add_i32 s8, s27, 0xc000
	s_add_i32 m0, s27, 0x8000
	v_lshl_add_u64 v[0:1], s[88:89], 0, v[0:1]
	v_lshl_add_u64 v[0:1], s[90:91], 0, v[4:5]
	s_mov_b32 m0, s8
	v_mov_b32_e32 v3, v145
	v_lshl_add_u64 v[0:1], s[88:89], 0, v[6:7]
	s_add_i32 m0, s27, 0x8400
	s_lshl_b32 s8, s26, 7
	v_lshl_add_u64 v[0:1], v[2:3], 1, s[90:91]
	s_add_i32 m0, s27, 0xc400
	s_mul_i32 s1, s1, 0xc000
	v_or_b32_e32 v0, s8, v144
	v_and_b32_e32 v1, 0x70, v19
	v_bitop3_b32 v173, v0, v1, 32 bitop3:0x36
	v_bitop3_b32 v174, v0, v1, 64 bitop3:0x36
	v_bitop3_b32 v175, v0, v1, s64 bitop3:0x36
	v_or_b32_e32 v0, s6, v14
	v_or3_b32 v0, v0, s7, v13
	v_mul_lo_u32 v0, v0, s35
	v_bitop3_b32 v172, s8, v1, v144 bitop3:0x36
	v_add_u32_e32 v172, v172, v171
	v_add_u32_e32 v173, v173, v171
	v_add_u32_e32 v174, v174, v171
	v_add_u32_e32 v175, v175, v171
	v_or3_b32 v0, v0, v15, v16
	v_mov_b32_e32 v1, v145
	s_add_i32 s6, s1, 0x6000
	v_lshlrev_b64 v[136:137], 1, v[0:1]
	v_mov_b32_e32 v0, s6
	v_mad_u32_u24 v0, v12, s35, v0
	v_or_b32_e32 v0, v0, v18
	v_lshlrev_b32_e32 v138, 1, v0
	v_mov_b32_e32 v0, s1
	v_mad_u32_u24 v0, v12, s35, v0
	v_or_b32_e32 v0, v0, v17
	s_waitcnt vmcnt(4) lgkmcnt(0)
	s_barrier
	v_lshlrev_b32_e32 v2, 2, v167
	v_lshlrev_b32_e32 v140, 1, v0
	s_mul_i32 s1, s26, 0x600
	v_add_u32_e32 v0, s0, v134
	v_and_b32_e32 v8, 0x100, v166
	v_sub_u32_e32 v0, v0, v2
	s_add_i32 s0, s1, 0
	v_mov_b32_e32 v65, v64
	v_mov_b32_e32 v66, v64
	v_mov_b32_e32 v67, v64
	v_mov_b32_e32 v68, v64
	v_mov_b32_e32 v69, v64
	v_mov_b32_e32 v70, v64
	v_mov_b32_e32 v71, v64
	v_mov_b32_e32 v72, v64
	v_mov_b32_e32 v73, v64
	v_mov_b32_e32 v74, v64
	v_mov_b32_e32 v75, v64
	v_mov_b32_e32 v76, v64
	v_mov_b32_e32 v77, v64
	v_mov_b32_e32 v78, v64
	v_mov_b32_e32 v79, v64
	v_add3_u32 v170, v21, v20, v8
	v_lshl_add_u32 v178, v0, 2, s0
	s_mov_b64 s[0:1], s[92:93]
	v_mov_b32_e32 v0, 0
	v_mov_b32_e32 v1, v176
	v_mov_b32_e32 v2, v176
	v_mov_b32_e32 v3, v176
	v_mov_b32_e32 v4, v176
	v_mov_b32_e32 v5, v176
	v_mov_b32_e32 v6, v176
	v_mov_b32_e32 v7, v176
	v_mov_b32_e32 v8, v176
	v_mov_b32_e32 v9, v176
	v_mov_b32_e32 v10, v176
	v_mov_b32_e32 v11, v176
	v_mov_b32_e32 v12, v176
	v_mov_b32_e32 v13, v176
	v_mov_b32_e32 v14, v176
	v_mov_b32_e32 v15, v176
	v_mov_b32_e32 v16, 0
	v_mov_b32_e32 v17, v176
	v_mov_b32_e32 v18, v176
	v_mov_b32_e32 v19, v176
	v_mov_b32_e32 v20, v176
	v_mov_b32_e32 v21, v176
	s_waitcnt vmcnt(0)
	s_branch .LBB0_312

; __global__ void __launch_bounds__(NWAVES * 64, 2) hybrid_fwd(Args args) {
;     ...
;                     if (sref <= 40.f) att::attn_unit<true>(bh / NH, hh, qb, (const att::bf16*)PROJ, (att::bf16*)MIX, BT, args.in[z + 10] + ll * 128, lam, 1.0f - lam_init, sref, args.in[z + 3] + (size_t)ll * 3 * CONVW, pr * 8 + half * 4, (char*)lds);
;                     else att::attn_unit<false>(bh / NH, hh, qb, (const att::bf16*)PROJ, (att::bf16*)MIX, BT, args.in[z + 10] + ll * 128, lam, 1.0f - lam_init, 0.f, args.in[z + 3] + (size_t)ll * 3 * CONVW, pr * 8 + half * 4, (char*)lds);
.LBB0_341:
	s_andn2_saveexec_b64 s[84:85], s[40:41]
	s_cbranch_execz .LBB0_300
	s_waitcnt vmcnt(0)
	s_barrier
	v_mov_b32_e32 v0, v169
	s_nop 0
	v_readfirstlane_b32 s25, v0
	v_cmp_gt_i32_e32 vcc, s33, v0
	s_and_saveexec_b64 s[0:1], vcc
	s_cbranch_execz .LBB0_350
	v_max_i32_e32 v1, 0x100, v0
	v_sub_u32_e32 v1, v1, v0
	v_add_u32_e32 v1, 0x1ff, v1
	s_movk_i32 s6, 0x1ff
	v_cmp_lt_u32_e32 vcc, s6, v1
	s_mov_b64 s[8:9], -1
	v_mov_b32_e32 v2, v0
	s_and_saveexec_b64 s[6:7], vcc
	s_cbranch_execz .LBB0_347
	v_lshrrev_b32_e32 v1, 9, v1
	v_add_u32_e32 v4, 1, v1
	v_and_b32_e32 v5, 0xfffffe, v4
	v_add_u32_e32 v1, 0x200, v0
	v_lshl_add_u32 v6, v0, 2, s57
	s_mov_b64 s[8:9], 0
	v_mov_b32_e32 v7, v5
	v_mov_b64_e32 v[2:3], v[0:1]
